# pool GEMM: skip structurally-zero K blocks of block-diagonal pool weights (guarded on gridDim==256)
# speedup vs baseline: 1.0274x; 1.0026x over previous
.LBB0_490:
	s_not_b32 s0, s82
	s_add_i32 s26, s71, s0
	s_cmpk_gt_i32 s26, 0xbf
	v_readfirstlane_b32 s44, v198
	s_cbranch_scc1 .LBB0_506
	s_mov_b32 s1, 0xffffe0
	v_and_or_b32 v0, v178, s1, v182
	v_or3_b32 v0, v0, v181, v180
	v_mul_u32_u24_e32 v0, 0x300, v0
	s_movk_i32 s0, 0x300
	s_waitcnt lgkmcnt(0)
	s_add_u32 s45, s38, 0x2112b400
	v_add_lshl_u32 v8, v0, v179, 1
	v_mul_lo_u32 v0, v178, s0
	s_addc_u32 s46, s39, 0
	v_add_lshl_u32 v200, v179, v0, 1
	v_and_or_b32 v0, v173, s1, v177
	s_add_u32 s47, s38, 0x1880000
	v_or3_b32 v0, v0, v176, v175
	s_addc_u32 s48, s39, 0
	v_mul_u32_u24_e32 v0, 0x300, v0
	s_ashr_i32 s50, s26, 31
	v_add_lshl_u32 v194, v0, v174, 1
	v_mul_lo_u32 v0, v173, s0
	s_lshr_b32 s0, s50, 29
	s_add_i32 s0, s26, s0
	s_ashr_i32 s21, s44, 6
	s_ashr_i32 s1, s0, 3
	s_and_b32 s0, s0, -8
	s_ashr_i32 s34, s44, 8
	s_lshl_b32 s49, s21, 10
	s_sub_i32 s0, s26, s0
	s_cmp_lt_i32 s0, 0
	s_cselect_b32 s2, 25, 24
	s_mul_i32 s0, s0, s2
	s_add_i32 s0, s0, s1
	s_mul_hi_i32 s1, s0, 0x2aaaaaab
	s_lshr_b32 s2, s1, 31
	s_ashr_i32 s1, s1, 2
	s_add_i32 s1, s1, s2
	s_lshl_b32 s2, s1, 3
	s_mul_i32 s1, s1, 24
	s_sub_i32 s0, s0, s1
	s_bfe_i32 s1, s0, 0x80000
	s_bfe_u32 s1, s1, 0x3000c
	s_add_i32 s1, s0, s1
	s_bfe_i32 s3, s1, 0x80000
	s_and_b32 s1, s1, 0xf8
	s_sub_i32 s0, s0, s1
	s_sext_i32_i16 s3, s3
	s_sext_i32_i8 s0, s0
	s_add_i32 s19, s2, s0
	s_ashr_i32 s2, s3, 3
	s_lshr_b32 s8, s3, 3
	s_mul_hi_i32 s3, s2, 0x60000
	s_mul_i32 s2, s2, 0x60000
	s_add_u32 s2, s47, s2
	s_addc_u32 s3, s48, s3
	s_mov_b32 s98, 0
	s_mov_b32 s99, -2
	s_cmpk_lg_i32 s71, 0x100
	s_cbranch_scc1 .Lpk_skip
	s_cmp_eq_u32 s8, 1
	s_cselect_b32 s98, 0x100, 0
	s_cselect_b32 s99, 2, 4
	s_cmp_eq_u32 s8, 2
	s_cselect_b32 s98, 0x300, s98
.Lpk_skip:
	s_add_u32 s2, s2, s98
	s_addc_u32 s3, s3, 0
	s_add_i32 s51, s49, 0
	s_add_i32 m0, s51, 0x10000
	s_mul_i32 s0, s19, 0x60000
	global_load_lds_dwordx4 v194, s[2:3]
	s_add_i32 m0, s51, 0x12000
	s_mul_hi_i32 s1, s19, 0x60000
	s_add_u32 s0, s45, s0
	v_add_lshl_u32 v202, v174, v0, 1
	global_load_lds_dwordx4 v8, s[2:3]
	s_addc_u32 s1, s46, s1
	s_add_u32 s0, s0, s98
	s_addc_u32 s1, s1, 0
	s_mov_b32 m0, s51
	s_add_i32 s52, s51, 0x2000
	global_load_lds_dwordx4 v202, s[0:1]
	s_mov_b32 m0, s52
	s_add_u32 s4, s2, 0x30000
	global_load_lds_dwordx4 v200, s[0:1]
	s_addc_u32 s5, s3, 0
	s_add_i32 m0, s51, 0x14000
	v_readlane_b32 s10, v254, 31
	global_load_lds_dwordx4 v194, s[4:5]
	s_add_i32 m0, s51, 0x16000
	v_readlane_b32 s11, v254, 32
	global_load_lds_dwordx4 v8, s[4:5]
	s_add_u32 s4, s0, 0x30000
	s_addc_u32 s5, s1, 0
	s_add_i32 s53, s51, 0x4000
	s_mov_b32 m0, s53
	s_add_i32 s54, s51, 0x6000
	global_load_lds_dwordx4 v202, s[4:5]
	s_mov_b32 m0, s54
	v_mov_b32_e32 v9, v195
	global_load_lds_dwordx4 v200, s[4:5]
	s_load_dwordx4 s[4:7], s[10:11], 0x70
	v_mov_b32_e32 v203, v195
	v_mov_b32_e32 v201, v195
	v_lshl_add_u64 v[6:7], s[2:3], 0, v[194:195]
	v_lshl_add_u64 v[4:5], s[2:3], 0, v[8:9]
	v_lshl_add_u64 v[2:3], s[0:1], 0, v[202:203]
	s_cmp_lg_u32 s34, 1
	v_lshl_add_u64 v[0:1], s[0:1], 0, v[200:201]
	s_cbranch_scc1 .LBB0_493
	s_barrier

.LBB0_500:
	s_add_u32 s21, s2, 0x100
	v_mov_b32_e32 v0, 0
	s_addc_u32 s36, s3, 0
	s_mov_b32 s60, s99
	v_mov_b32_e32 v1, v0
	v_mov_b32_e32 v2, v0
	v_mov_b32_e32 v3, v0
	v_mov_b32_e32 v4, v0
	v_mov_b32_e32 v5, v0
	v_mov_b32_e32 v6, v0
	v_mov_b32_e32 v7, v0
	v_mov_b32_e32 v22, v0
	v_mov_b32_e32 v23, v0
	v_mov_b32_e32 v24, v0
	v_mov_b32_e32 v25, v0
	v_mov_b32_e32 v26, v0
	v_mov_b32_e32 v27, v0
	v_mov_b32_e32 v28, v0
	v_mov_b32_e32 v29, v0
	v_mov_b32_e32 v54, v0
	v_mov_b32_e32 v55, v0
	v_mov_b32_e32 v56, v0
	v_mov_b32_e32 v57, v0
	v_mov_b32_e32 v58, v0
	v_mov_b32_e32 v59, v0
	v_mov_b32_e32 v60, v0
	v_mov_b32_e32 v61, v0
	v_mov_b32_e32 v86, v0
	v_mov_b32_e32 v87, v0
	v_mov_b32_e32 v88, v0
	v_mov_b32_e32 v89, v0
	v_mov_b32_e32 v90, v0
	v_mov_b32_e32 v91, v0
	v_mov_b32_e32 v92, v0
	v_mov_b32_e32 v93, v0
	v_mov_b32_e32 v14, v0
	v_mov_b32_e32 v15, v0
	v_mov_b32_e32 v16, v0
	v_mov_b32_e32 v17, v0
	v_mov_b32_e32 v18, v0
	v_mov_b32_e32 v19, v0
	v_mov_b32_e32 v20, v0
	v_mov_b32_e32 v21, v0
	v_mov_b32_e32 v30, v0
	v_mov_b32_e32 v31, v0
	v_mov_b32_e32 v32, v0
	v_mov_b32_e32 v33, v0
	v_mov_b32_e32 v34, v0
	v_mov_b32_e32 v35, v0
	v_mov_b32_e32 v36, v0
	v_mov_b32_e32 v37, v0
	v_mov_b32_e32 v78, v0
	v_mov_b32_e32 v79, v0
	v_mov_b32_e32 v80, v0
	v_mov_b32_e32 v81, v0
	v_mov_b32_e32 v82, v0
	v_mov_b32_e32 v83, v0
	v_mov_b32_e32 v84, v0
	v_mov_b32_e32 v85, v0
	v_mov_b32_e32 v94, v0
	v_mov_b32_e32 v95, v0
	v_mov_b32_e32 v96, v0
	v_mov_b32_e32 v97, v0
	v_mov_b32_e32 v98, v0
	v_mov_b32_e32 v99, v0
	v_mov_b32_e32 v100, v0
	v_mov_b32_e32 v101, v0
	v_mov_b32_e32 v102, v0
	v_mov_b32_e32 v103, v0
	v_mov_b32_e32 v104, v0
	v_mov_b32_e32 v105, v0
	v_mov_b32_e32 v106, v0
	v_mov_b32_e32 v107, v0
	v_mov_b32_e32 v108, v0
	v_mov_b32_e32 v109, v0
	v_mov_b32_e32 v118, v0
	v_mov_b32_e32 v119, v0
	v_mov_b32_e32 v120, v0
	v_mov_b32_e32 v121, v0
	v_mov_b32_e32 v122, v0
	v_mov_b32_e32 v123, v0
	v_mov_b32_e32 v124, v0
	v_mov_b32_e32 v125, v0
	v_mov_b32_e32 v138, v0
	v_mov_b32_e32 v139, v0
	v_mov_b32_e32 v140, v0
	v_mov_b32_e32 v141, v0
	v_mov_b32_e32 v142, v0
	v_mov_b32_e32 v143, v0
	v_mov_b32_e32 v144, v0
	v_mov_b32_e32 v145, v0
	v_mov_b32_e32 v162, v0
	v_mov_b32_e32 v163, v0
	v_mov_b32_e32 v164, v0
	v_mov_b32_e32 v165, v0
	v_mov_b32_e32 v166, v0
	v_mov_b32_e32 v167, v0
	v_mov_b32_e32 v168, v0
	v_mov_b32_e32 v169, v0
	v_mov_b32_e32 v110, v0
	v_mov_b32_e32 v111, v0
	v_mov_b32_e32 v112, v0
	v_mov_b32_e32 v113, v0
	v_mov_b32_e32 v114, v0
	v_mov_b32_e32 v115, v0
	v_mov_b32_e32 v116, v0
	v_mov_b32_e32 v117, v0
	v_mov_b32_e32 v126, v0
	v_mov_b32_e32 v127, v0
	v_mov_b32_e32 v128, v0
	v_mov_b32_e32 v129, v0
	v_mov_b32_e32 v130, v0
	v_mov_b32_e32 v131, v0
	v_mov_b32_e32 v132, v0
	v_mov_b32_e32 v133, v0
	v_mov_b32_e32 v150, v0
	v_mov_b32_e32 v151, v0
	v_mov_b32_e32 v152, v0
	v_mov_b32_e32 v153, v0
	v_mov_b32_e32 v154, v0
	v_mov_b32_e32 v155, v0
	v_mov_b32_e32 v156, v0
	v_mov_b32_e32 v157, v0
	v_mov_b32_e32 v178, v0
	v_mov_b32_e32 v179, v0
	v_mov_b32_e32 v180, v0
	v_mov_b32_e32 v181, v0
	v_mov_b32_e32 v182, v0
	v_mov_b32_e32 v183, v0
	v_mov_b32_e32 v184, v0
	v_mov_b32_e32 v185, v0
